# static s_setprio 1 for waves 0-3 (mirror half) around each GEMM K-loop, per-phase flips removed
# baseline (speedup 1.0000x reference)
; template <class Epi, class Sched, bool ALIGN_EPI = false, bool SP2 = false>
; __device__ __forceinline__ void gemm_phase(PG8_LAS unsigned char* lds, const Gemm g, const Sched& S, const Epi& E, const int tid) {
;     ...
;         const bool has_next = S.next(ui + 1, nxt);
;         const char* nA = has_next ? (const char*)g.A + (size_t)nxt.pm * tstep : cA; const char* nB = has_next ? (const char*)g.Bt + (size_t)nxt.pn * tstep : cB;
;     ...
; #pragma unroll
;         for (int a = 0; a < 2; ++a)
; #pragma unroll
;             for (int b = 0; b < 2; ++b)
; #pragma unroll
;                 for (int m = 0; m < 4; ++m)
; #pragma unroll
;                     for (int n = 0; n < 2; ++n) acc[a][b][m][n] = (f32x4){0.f, 0.f, 0.f, 0.f};
;         cur = nxt; cA = nA; cB = nB; ++ui;
.LBB0_98:
	s_ashr_i32 s13, s12, 31
	s_lshl_b64 s[14:15], s[12:13], 19
	s_add_u32 s14, s27, s14
	s_addc_u32 s15, s34, s15
	s_and_b64 s[16:17], s[2:3], exec
	s_cselect_b32 s13, s15, s19
	s_cselect_b32 s45, s14, s18
	s_ashr_i32 s11, s10, 31
	s_lshl_b64 s[16:17], s[10:11], 19
	s_add_u32 s16, s24, s16
	s_addc_u32 s17, s25, s17
	s_and_b64 s[22:23], s[2:3], exec
	s_cselect_b32 s11, s17, s21
	s_cselect_b32 s46, s16, s20
	s_add_u32 s18, s18, 0x40080
	s_addc_u32 s19, s19, 0
	s_add_u32 s47, s20, 0x100
	v_mov_b32_e32 v4, 0
	s_addc_u32 s48, s21, 0
	s_mov_b32 s49, -2
	v_mov_b64_e32 v[4:5], 0
	v_mov_b64_e32 v[6:7], 0
	v_mov_b64_e32 v[8:9], 0
	v_mov_b64_e32 v[10:11], 0
	v_mov_b64_e32 v[12:13], 0
	v_mov_b64_e32 v[14:15], 0
	v_mov_b64_e32 v[16:17], 0
	v_mov_b64_e32 v[18:19], 0
	v_mov_b64_e32 v[20:21], 0
	v_mov_b64_e32 v[22:23], 0
	v_mov_b64_e32 v[24:25], 0
	v_mov_b64_e32 v[26:27], 0
	v_mov_b64_e32 v[28:29], 0
	v_mov_b64_e32 v[30:31], 0
	v_mov_b64_e32 v[32:33], 0
	v_mov_b64_e32 v[34:35], 0
	v_mov_b64_e32 v[36:37], 0
	v_mov_b64_e32 v[38:39], 0
	v_mov_b64_e32 v[40:41], 0
	v_mov_b64_e32 v[42:43], 0
	v_mov_b64_e32 v[44:45], 0
	v_mov_b64_e32 v[46:47], 0
	v_mov_b64_e32 v[48:49], 0
	v_mov_b64_e32 v[50:51], 0
	v_mov_b64_e32 v[52:53], 0
	v_mov_b64_e32 v[54:55], 0
	v_mov_b64_e32 v[56:57], 0
	v_mov_b64_e32 v[58:59], 0
	v_mov_b64_e32 v[60:61], 0
	v_mov_b64_e32 v[62:63], 0
	v_mov_b64_e32 v[64:65], 0
	v_mov_b64_e32 v[66:67], 0
	v_mov_b64_e32 v[68:69], 0
	v_mov_b64_e32 v[70:71], 0
	v_mov_b64_e32 v[72:73], 0
	v_mov_b64_e32 v[74:75], 0
	v_mov_b64_e32 v[76:77], 0
	v_mov_b64_e32 v[78:79], 0
	v_mov_b64_e32 v[80:81], 0
	v_mov_b64_e32 v[82:83], 0
	v_mov_b64_e32 v[84:85], 0
	v_mov_b64_e32 v[86:87], 0
	v_mov_b64_e32 v[88:89], 0
	v_mov_b64_e32 v[90:91], 0
	v_mov_b64_e32 v[92:93], 0
	v_mov_b64_e32 v[94:95], 0
	v_mov_b64_e32 v[96:97], 0
	v_mov_b64_e32 v[98:99], 0
	v_mov_b64_e32 v[100:101], 0
	v_mov_b64_e32 v[102:103], 0
	v_mov_b64_e32 v[104:105], 0
	v_mov_b64_e32 v[106:107], 0
	v_mov_b64_e32 v[108:109], 0
	v_mov_b64_e32 v[110:111], 0
	v_mov_b64_e32 v[112:113], 0
	v_mov_b64_e32 v[114:115], 0
	v_mov_b64_e32 v[128:129], 0
	v_mov_b64_e32 v[130:131], 0
	v_mov_b64_e32 v[136:137], 0
	v_mov_b64_e32 v[138:139], 0
	v_mov_b64_e32 v[140:141], 0
	v_mov_b64_e32 v[142:143], 0
	v_mov_b64_e32 v[144:145], 0
	v_mov_b64_e32 v[146:147], 0
	s_cmp_ge_u32 s92, 4
	s_cbranch_scc1 .Lprio_skip0
	s_setprio 1

; template <class Epi, class Sched, bool ALIGN_EPI = false, bool SP2 = false>
; __device__ __forceinline__ void gemm_phase(PG8_LAS unsigned char* lds, const Gemm g, const Sched& S, const Epi& E, const int tid) {
;     ...
;         const bool has_next = S.next(ui + 1, nxt);
;         const char* nA = has_next ? (const char*)g.A + (size_t)nxt.pm * tstep : cA; const char* nB = has_next ? (const char*)g.Bt + (size_t)nxt.pn * tstep : cB;
;     ...
; #pragma unroll
;         for (int a = 0; a < 2; ++a)
; #pragma unroll
;             for (int b = 0; b < 2; ++b)
; #pragma unroll
;                 for (int m = 0; m < 4; ++m)
; #pragma unroll
;                     for (int n = 0; n < 2; ++n) acc[a][b][m][n] = (f32x4){0.f, 0.f, 0.f, 0.f};
;         cur = nxt; cA = nA; cB = nB; ++ui;
.LBB0_292:
	s_ashr_i32 s17, s16, 31
	s_lshl_b64 s[18:19], s[16:17], 19
	s_add_u32 s18, s34, s18
	s_addc_u32 s19, s40, s19
	s_and_b64 s[20:21], s[4:5], exec
	s_cselect_b32 s17, s19, s3
	s_cselect_b32 s23, s18, s2
	s_ashr_i32 s15, s14, 31
	s_lshl_b64 s[20:21], s[14:15], 19
	s_add_u32 s20, s41, s20
	s_addc_u32 s21, s42, s21
	s_and_b64 s[36:37], s[4:5], exec
	s_cselect_b32 s15, s21, s27
	s_cselect_b32 s51, s20, s26
	s_add_u32 s2, s2, 0x40080
	s_addc_u32 s3, s3, 0
	s_add_u32 s52, s26, 0x100
	v_mov_b32_e32 v12, 0
	s_addc_u32 s53, s27, 0
	s_mov_b32 s54, -2
	v_mov_b64_e32 v[4:5], 0
	v_mov_b64_e32 v[6:7], 0
	v_mov_b64_e32 v[8:9], 0
	v_mov_b64_e32 v[10:11], 0
	v_mov_b64_e32 v[12:13], 0
	v_mov_b64_e32 v[14:15], 0
	v_mov_b64_e32 v[16:17], 0
	v_mov_b64_e32 v[18:19], 0
	v_mov_b64_e32 v[20:21], 0
	v_mov_b64_e32 v[22:23], 0
	v_mov_b64_e32 v[24:25], 0
	v_mov_b64_e32 v[26:27], 0
	v_mov_b64_e32 v[28:29], 0
	v_mov_b64_e32 v[30:31], 0
	v_mov_b64_e32 v[32:33], 0
	v_mov_b64_e32 v[34:35], 0
	v_mov_b64_e32 v[36:37], 0
	v_mov_b64_e32 v[38:39], 0
	v_mov_b64_e32 v[40:41], 0
	v_mov_b64_e32 v[42:43], 0
	v_mov_b64_e32 v[44:45], 0
	v_mov_b64_e32 v[46:47], 0
	v_mov_b64_e32 v[48:49], 0
	v_mov_b64_e32 v[50:51], 0
	v_mov_b64_e32 v[52:53], 0
	v_mov_b64_e32 v[54:55], 0
	v_mov_b64_e32 v[56:57], 0
	v_mov_b64_e32 v[58:59], 0
	v_mov_b64_e32 v[60:61], 0
	v_mov_b64_e32 v[62:63], 0
	v_mov_b64_e32 v[64:65], 0
	v_mov_b64_e32 v[66:67], 0
	v_mov_b64_e32 v[68:69], 0
	v_mov_b64_e32 v[70:71], 0
	v_mov_b64_e32 v[72:73], 0
	v_mov_b64_e32 v[74:75], 0
	v_mov_b64_e32 v[76:77], 0
	v_mov_b64_e32 v[78:79], 0
	v_mov_b64_e32 v[80:81], 0
	v_mov_b64_e32 v[82:83], 0
	v_mov_b64_e32 v[84:85], 0
	v_mov_b64_e32 v[86:87], 0
	v_mov_b64_e32 v[88:89], 0
	v_mov_b64_e32 v[90:91], 0
	v_mov_b64_e32 v[92:93], 0
	v_mov_b64_e32 v[94:95], 0
	v_mov_b64_e32 v[96:97], 0
	v_mov_b64_e32 v[98:99], 0
	v_mov_b64_e32 v[100:101], 0
	v_mov_b64_e32 v[102:103], 0
	v_mov_b64_e32 v[104:105], 0
	v_mov_b64_e32 v[106:107], 0
	v_mov_b64_e32 v[108:109], 0
	v_mov_b64_e32 v[110:111], 0
	v_mov_b64_e32 v[112:113], 0
	v_mov_b64_e32 v[114:115], 0
	v_mov_b64_e32 v[116:117], 0
	v_mov_b64_e32 v[118:119], 0
	v_mov_b64_e32 v[120:121], 0
	v_mov_b64_e32 v[122:123], 0
	v_mov_b64_e32 v[124:125], 0
	v_mov_b64_e32 v[126:127], 0
	v_mov_b64_e32 v[128:129], 0
	v_mov_b64_e32 v[130:131], 0
	s_cmp_ge_u32 s92, 4
	s_cbranch_scc1 .Lprio_skip1
	s_setprio 1

; template <class Epi, class Sched, bool ALIGN_EPI = false, bool SP2 = false>
; __device__ __forceinline__ void gemm_phase(PG8_LAS unsigned char* lds, const Gemm g, const Sched& S, const Epi& E, const int tid) {
;     ...
; #pragma unroll
;         for (int a = 0; a < 2; ++a)
; #pragma unroll
;             for (int b = 0; b < 2; ++b)
; #pragma unroll
;                 for (int m = 0; m < 4; ++m)
; #pragma unroll
;                     for (int n = 0; n < 2; ++n) acc[a][b][m][n] = (f32x4){0.f, 0.f, 0.f, 0.f};
;         cur = nxt; cA = nA; cB = nB; ++ui;
.LBB0_475:
	s_add_u32 s6, s6, 0x80
	s_addc_u32 s7, s7, 0
	s_add_u32 s78, s58, 0x100
	v_mov_b32_e32 v4, 0
	s_addc_u32 s79, s59, 0
	s_mov_b32 s58, 0
	v_mov_b64_e32 v[4:5], 0
	v_mov_b64_e32 v[6:7], 0
	v_mov_b64_e32 v[8:9], 0
	v_mov_b64_e32 v[10:11], 0
	v_mov_b64_e32 v[12:13], 0
	v_mov_b64_e32 v[14:15], 0
	v_mov_b64_e32 v[16:17], 0
	v_mov_b64_e32 v[18:19], 0
	v_mov_b64_e32 v[20:21], 0
	v_mov_b64_e32 v[22:23], 0
	v_mov_b64_e32 v[24:25], 0
	v_mov_b64_e32 v[26:27], 0
	v_mov_b64_e32 v[28:29], 0
	v_mov_b64_e32 v[30:31], 0
	v_mov_b64_e32 v[32:33], 0
	v_mov_b64_e32 v[34:35], 0
	v_mov_b64_e32 v[36:37], 0
	v_mov_b64_e32 v[38:39], 0
	v_mov_b64_e32 v[40:41], 0
	v_mov_b64_e32 v[42:43], 0
	v_mov_b64_e32 v[44:45], 0
	v_mov_b64_e32 v[46:47], 0
	v_mov_b64_e32 v[48:49], 0
	v_mov_b64_e32 v[50:51], 0
	v_mov_b64_e32 v[52:53], 0
	v_mov_b64_e32 v[54:55], 0
	v_mov_b64_e32 v[56:57], 0
	v_mov_b64_e32 v[58:59], 0
	v_mov_b64_e32 v[60:61], 0
	v_mov_b64_e32 v[62:63], 0
	v_mov_b64_e32 v[64:65], 0
	v_mov_b64_e32 v[66:67], 0
	v_mov_b64_e32 v[68:69], 0
	v_mov_b64_e32 v[70:71], 0
	v_mov_b64_e32 v[72:73], 0
	v_mov_b64_e32 v[74:75], 0
	v_mov_b64_e32 v[76:77], 0
	v_mov_b64_e32 v[78:79], 0
	v_mov_b64_e32 v[80:81], 0
	v_mov_b64_e32 v[82:83], 0
	v_mov_b64_e32 v[84:85], 0
	v_mov_b64_e32 v[86:87], 0
	v_mov_b64_e32 v[88:89], 0
	v_mov_b64_e32 v[90:91], 0
	v_mov_b64_e32 v[92:93], 0
	v_mov_b64_e32 v[94:95], 0
	v_mov_b64_e32 v[96:97], 0
	v_mov_b64_e32 v[98:99], 0
	v_mov_b64_e32 v[100:101], 0
	v_mov_b64_e32 v[102:103], 0
	v_mov_b64_e32 v[104:105], 0
	v_mov_b64_e32 v[106:107], 0
	v_mov_b64_e32 v[108:109], 0
	v_mov_b64_e32 v[110:111], 0
	v_mov_b64_e32 v[112:113], 0
	v_mov_b64_e32 v[114:115], 0
	v_mov_b64_e32 v[116:117], 0
	v_mov_b64_e32 v[118:119], 0
	v_mov_b64_e32 v[120:121], 0
	v_mov_b64_e32 v[122:123], 0
	v_mov_b64_e32 v[124:125], 0
	v_mov_b64_e32 v[126:127], 0
	v_mov_b64_e32 v[128:129], 0
	v_mov_b64_e32 v[130:131], 0
	s_cmp_ge_u32 s92, 4
	s_cbranch_scc1 .Lprio_skip2
	s_setprio 1

; template <class Epi, class Sched, bool ALIGN_EPI = false, bool SP2 = false>
; __device__ __forceinline__ void gemm_phase(PG8_LAS unsigned char* lds, const Gemm g, const Sched& S, const Epi& E, const int tid) {
;     ...
;         const bool has_next = S.next(ui + 1, nxt);
;         const char* nA = has_next ? (const char*)g.A + (size_t)nxt.pm * tstep : cA; const char* nB = has_next ? (const char*)g.Bt + (size_t)nxt.pn * tstep : cB;
;     ...
; #pragma unroll
;         for (int a = 0; a < 2; ++a)
; #pragma unroll
;             for (int b = 0; b < 2; ++b)
; #pragma unroll
;                 for (int m = 0; m < 4; ++m)
; #pragma unroll
;                     for (int n = 0; n < 2; ++n) acc[a][b][m][n] = (f32x4){0.f, 0.f, 0.f, 0.f};
;         cur = nxt; cA = nA; cB = nB; ++ui;
.LBB0_521:
	s_ashr_i32 s13, s12, 31
	s_lshl_b64 s[14:15], s[12:13], 19
	s_add_u32 s14, s26, s14
	s_addc_u32 s15, s27, s15
	s_and_b64 s[16:17], s[2:3], exec
	s_cselect_b32 s13, s15, s19
	s_cselect_b32 s47, s14, s18
	s_ashr_i32 s11, s10, 31
	s_lshl_b64 s[16:17], s[10:11], 19
	s_add_u32 s16, s34, s16
	s_addc_u32 s17, s36, s17
	s_and_b64 s[22:23], s[2:3], exec
	s_cselect_b32 s11, s17, s21
	s_cselect_b32 s48, s16, s20
	s_add_u32 s18, s18, 0x40080
	s_addc_u32 s19, s19, 0
	s_add_u32 s49, s20, 0x100
	v_mov_b32_e32 v4, 0
	s_addc_u32 s50, s21, 0
	s_mov_b32 s51, -2
	v_mov_b64_e32 v[4:5], 0
	v_mov_b64_e32 v[6:7], 0
	v_mov_b64_e32 v[8:9], 0
	v_mov_b64_e32 v[10:11], 0
	v_mov_b64_e32 v[12:13], 0
	v_mov_b64_e32 v[14:15], 0
	v_mov_b64_e32 v[16:17], 0
	v_mov_b64_e32 v[18:19], 0
	v_mov_b64_e32 v[20:21], 0
	v_mov_b64_e32 v[22:23], 0
	v_mov_b64_e32 v[24:25], 0
	v_mov_b64_e32 v[26:27], 0
	v_mov_b64_e32 v[28:29], 0
	v_mov_b64_e32 v[30:31], 0
	v_mov_b64_e32 v[32:33], 0
	v_mov_b64_e32 v[34:35], 0
	v_mov_b64_e32 v[36:37], 0
	v_mov_b64_e32 v[38:39], 0
	v_mov_b64_e32 v[40:41], 0
	v_mov_b64_e32 v[42:43], 0
	v_mov_b64_e32 v[44:45], 0
	v_mov_b64_e32 v[46:47], 0
	v_mov_b64_e32 v[48:49], 0
	v_mov_b64_e32 v[50:51], 0
	v_mov_b64_e32 v[52:53], 0
	v_mov_b64_e32 v[54:55], 0
	v_mov_b64_e32 v[56:57], 0
	v_mov_b64_e32 v[58:59], 0
	v_mov_b64_e32 v[60:61], 0
	v_mov_b64_e32 v[62:63], 0
	v_mov_b64_e32 v[64:65], 0
	v_mov_b64_e32 v[66:67], 0
	v_mov_b64_e32 v[68:69], 0
	v_mov_b64_e32 v[70:71], 0
	v_mov_b64_e32 v[72:73], 0
	v_mov_b64_e32 v[74:75], 0
	v_mov_b64_e32 v[76:77], 0
	v_mov_b64_e32 v[78:79], 0
	v_mov_b64_e32 v[80:81], 0
	v_mov_b64_e32 v[82:83], 0
	v_mov_b64_e32 v[84:85], 0
	v_mov_b64_e32 v[86:87], 0
	v_mov_b64_e32 v[88:89], 0
	v_mov_b64_e32 v[90:91], 0
	v_mov_b64_e32 v[92:93], 0
	v_mov_b64_e32 v[94:95], 0
	v_mov_b64_e32 v[96:97], 0
	v_mov_b64_e32 v[98:99], 0
	v_mov_b64_e32 v[100:101], 0
	v_mov_b64_e32 v[102:103], 0
	v_mov_b64_e32 v[104:105], 0
	v_mov_b64_e32 v[106:107], 0
	v_mov_b64_e32 v[108:109], 0
	v_mov_b64_e32 v[110:111], 0
	v_mov_b64_e32 v[112:113], 0
	v_mov_b64_e32 v[114:115], 0
	v_mov_b64_e32 v[116:117], 0
	v_mov_b64_e32 v[118:119], 0
	v_mov_b64_e32 v[120:121], 0
	v_mov_b64_e32 v[122:123], 0
	v_mov_b64_e32 v[124:125], 0
	v_mov_b64_e32 v[126:127], 0
	v_mov_b64_e32 v[128:129], 0
	v_mov_b64_e32 v[130:131], 0
	s_cmp_ge_u32 s92, 4
	s_cbranch_scc1 .Lprio_skip3
	s_setprio 1

; template <class Epi, class Sched, bool ALIGN_EPI = false, bool SP2 = false>
; __device__ __forceinline__ void gemm_phase(PG8_LAS unsigned char* lds, const Gemm g, const Sched& S, const Epi& E, const int tid) {
;     ...
;         const bool has_next = S.next(ui + 1, nxt);
;         const char* nA = has_next ? (const char*)g.A + (size_t)nxt.pm * tstep : cA; const char* nB = has_next ? (const char*)g.Bt + (size_t)nxt.pn * tstep : cB;
;     ...
; #pragma unroll
;         for (int a = 0; a < 2; ++a)
; #pragma unroll
;             for (int b = 0; b < 2; ++b)
; #pragma unroll
;                 for (int m = 0; m < 4; ++m)
; #pragma unroll
;                     for (int n = 0; n < 2; ++n) acc[a][b][m][n] = (f32x4){0.f, 0.f, 0.f, 0.f};
;         cur = nxt; cA = nA; cB = nB; ++ui;
.LBB0_841:
	s_ashr_i32 s13, s12, 31
	s_lshl_b64 s[14:15], s[12:13], 19
	s_add_u32 s14, s34, s14
	s_addc_u32 s15, s36, s15
	s_and_b64 s[16:17], s[38:39], exec
	s_cselect_b32 s13, s15, s23
	s_cselect_b32 s19, s14, s22
	s_ashr_i32 s11, s10, 31
	s_lshl_b64 s[16:17], s[10:11], 19
	s_add_u32 s16, s4, s16
	s_addc_u32 s17, s5, s17
	s_and_b64 s[26:27], s[38:39], exec
	s_cselect_b32 s11, s17, s25
	s_cselect_b32 s46, s16, s24
	s_add_u32 s22, s22, 0x40080
	s_addc_u32 s23, s23, 0
	s_add_u32 s47, s24, 0x100
	v_mov_b32_e32 v4, 0
	s_addc_u32 s48, s25, 0
	s_mov_b32 s49, -2
	v_mov_b64_e32 v[4:5], 0
	v_mov_b64_e32 v[6:7], 0
	v_mov_b64_e32 v[8:9], 0
	v_mov_b64_e32 v[10:11], 0
	v_mov_b64_e32 v[12:13], 0
	v_mov_b64_e32 v[14:15], 0
	v_mov_b64_e32 v[16:17], 0
	v_mov_b64_e32 v[18:19], 0
	v_mov_b64_e32 v[20:21], 0
	v_mov_b64_e32 v[22:23], 0
	v_mov_b64_e32 v[24:25], 0
	v_mov_b64_e32 v[26:27], 0
	v_mov_b64_e32 v[28:29], 0
	v_mov_b64_e32 v[30:31], 0
	v_mov_b64_e32 v[32:33], 0
	v_mov_b64_e32 v[34:35], 0
	v_mov_b64_e32 v[36:37], 0
	v_mov_b64_e32 v[38:39], 0
	v_mov_b64_e32 v[40:41], 0
	v_mov_b64_e32 v[42:43], 0
	v_mov_b64_e32 v[44:45], 0
	v_mov_b64_e32 v[46:47], 0
	v_mov_b64_e32 v[48:49], 0
	v_mov_b64_e32 v[50:51], 0
	v_mov_b64_e32 v[52:53], 0
	v_mov_b64_e32 v[54:55], 0
	v_mov_b64_e32 v[56:57], 0
	v_mov_b64_e32 v[58:59], 0
	v_mov_b64_e32 v[60:61], 0
	v_mov_b64_e32 v[62:63], 0
	v_mov_b64_e32 v[64:65], 0
	v_mov_b64_e32 v[66:67], 0
	v_mov_b64_e32 v[68:69], 0
	v_mov_b64_e32 v[70:71], 0
	v_mov_b64_e32 v[72:73], 0
	v_mov_b64_e32 v[74:75], 0
	v_mov_b64_e32 v[76:77], 0
	v_mov_b64_e32 v[78:79], 0
	v_mov_b64_e32 v[80:81], 0
	v_mov_b64_e32 v[82:83], 0
	v_mov_b64_e32 v[84:85], 0
	v_mov_b64_e32 v[86:87], 0
	v_mov_b64_e32 v[88:89], 0
	v_mov_b64_e32 v[90:91], 0
	v_mov_b64_e32 v[92:93], 0
	v_mov_b64_e32 v[94:95], 0
	v_mov_b64_e32 v[96:97], 0
	v_mov_b64_e32 v[98:99], 0
	v_mov_b64_e32 v[100:101], 0
	v_mov_b64_e32 v[102:103], 0
	v_mov_b64_e32 v[104:105], 0
	v_mov_b64_e32 v[106:107], 0
	v_mov_b64_e32 v[108:109], 0
	v_mov_b64_e32 v[110:111], 0
	v_mov_b64_e32 v[112:113], 0
	v_mov_b64_e32 v[114:115], 0
	v_mov_b64_e32 v[116:117], 0
	v_mov_b64_e32 v[118:119], 0
	v_mov_b64_e32 v[120:121], 0
	v_mov_b64_e32 v[122:123], 0
	v_mov_b64_e32 v[124:125], 0
	v_mov_b64_e32 v[126:127], 0
	v_mov_b64_e32 v[128:129], 0
	v_mov_b64_e32 v[130:131], 0
	s_cmp_ge_u32 s92, 4
	s_cbranch_scc1 .Lprio_skip4
	s_setprio 1
